# v5 + MLA row-sum via v_pk_add_f32 (32 packed adds replace 64 scalar adds per tile)
# baseline (speedup 1.0000x reference)
; #define LAS __attribute__((address_space(3)))
; #define MFMA32(a, b, c) __builtin_amdgcn_mfma_f32_32x32x16_bf16((a), (b), (c), 0, 0, 0)
; DI s16x4 trread(LAS const char* p) { return __builtin_bit_cast(s16x4, __builtin_amdgcn_ds_read_tr16_b64_v4i16((LAS v4i16_t*)p)); }
; DI bf16x8 cat8(s16x4 lo, s16x4 hi) { return __builtin_shufflevector(lo, hi, 0, 1, 2, 3, 4, 5, 6, 7); }
; DI void mla_phase(const Args& A, LAS unsigned char* lds, int i, const int wv) {
;     ...
;             float ls = 0.f;
; #pragma unroll
;             for (int kt = 0; kt < 4; ++kt)
; #pragma unroll
;                 for (int rg = 0; rg < 16; ++rg) { p[kt][rg] = __builtin_amdgcn_exp2f(p[kt][rg]); ls += p[kt][rg]; }
;             l += ls;
; #pragma unroll
;             for (int kt = 0; kt < 4; ++kt)
; #pragma unroll
;                 for (int s = 0; s < 2; ++s) { const bf16x8 pb = pack8(p[kt], s);
; #pragma unroll
;                     for (int dt = 0; dt < 2; ++dt) { LAS const char* ad = (LAS const char*)vbp + (32 * kt + 16 * s + 4 * h + q_) * 144 + (32 * dt + 16 * blk) * 2 + 8 * p_;
;                         const bf16x8 va = cat8(trread(ad), trread(ad + 8 * 144)); o[dt] = MFMA32(va, pb, o[dt]); } }
.Lmla_a_norescale:
	v_exp_f32_e32 v112, v112
	v_exp_f32_e32 v113, v113
	v_exp_f32_e32 v114, v114
	v_exp_f32_e32 v115, v115
	v_exp_f32_e32 v116, v116
	v_exp_f32_e32 v117, v117
	v_exp_f32_e32 v118, v118
	v_exp_f32_e32 v119, v119
	v_pk_add_f32 v[14:15], v[112:113], v[114:115]
	v_pk_add_f32 v[14:15], v[14:15], v[116:117]
	v_pk_add_f32 v[14:15], v[14:15], v[118:119]
	v_cvt_pk_bf16_f32 v10, v112, v113
	v_cvt_pk_bf16_f32 v11, v114, v115
	v_cvt_pk_bf16_f32 v12, v116, v117
	v_cvt_pk_bf16_f32 v13, v118, v119
	ds_read_b64_tr_b16 v[116:117], v182 offset:28928
	ds_read_b64_tr_b16 v[118:119], v182 offset:30080
	v_exp_f32_e32 v120, v120
	v_exp_f32_e32 v121, v121
	v_exp_f32_e32 v122, v122
	v_exp_f32_e32 v123, v123
	v_exp_f32_e32 v124, v124
	v_exp_f32_e32 v125, v125
	v_exp_f32_e32 v126, v126
	v_exp_f32_e32 v127, v127
	v_pk_add_f32 v[14:15], v[14:15], v[120:121]
	v_pk_add_f32 v[14:15], v[14:15], v[122:123]
	v_pk_add_f32 v[14:15], v[14:15], v[124:125]
	v_pk_add_f32 v[14:15], v[14:15], v[126:127]
	v_cvt_pk_bf16_f32 v112, v120, v121
	v_cvt_pk_bf16_f32 v113, v122, v123
	v_cvt_pk_bf16_f32 v114, v124, v125
	v_cvt_pk_bf16_f32 v115, v126, v127
	ds_read_b64_tr_b16 v[120:121], v182 offset:28992
	ds_read_b64_tr_b16 v[122:123], v182 offset:30144
	s_nop 0
	v_mfma_f32_32x32x16_bf16 v[32:47], v[2:5], v[10:13], v[32:47]
	ds_read_b64_tr_b16 v[2:3], v182 offset:31232
	ds_read_b64_tr_b16 v[4:5], v182 offset:32384
	v_exp_f32_e32 v96, v96
	v_exp_f32_e32 v97, v97
	v_exp_f32_e32 v98, v98
	v_exp_f32_e32 v99, v99
	v_exp_f32_e32 v100, v100
	v_exp_f32_e32 v101, v101
	v_mfma_f32_32x32x16_bf16 v[16:31], v[6:9], v[10:13], v[16:31]
	ds_read_b64_tr_b16 v[6:7], v182 offset:31296
	ds_read_b64_tr_b16 v[8:9], v182 offset:32448
	v_exp_f32_e32 v102, v102
	v_exp_f32_e32 v103, v103
	v_pk_add_f32 v[14:15], v[14:15], v[96:97]
	v_pk_add_f32 v[14:15], v[14:15], v[98:99]
	v_pk_add_f32 v[14:15], v[14:15], v[100:101]
	v_pk_add_f32 v[14:15], v[14:15], v[102:103]
	v_cvt_pk_bf16_f32 v124, v96, v97
	v_cvt_pk_bf16_f32 v125, v98, v99
	v_cvt_pk_bf16_f32 v126, v100, v101
	v_cvt_pk_bf16_f32 v127, v102, v103
	s_waitcnt lgkmcnt(6)
	v_mfma_f32_32x32x16_bf16 v[32:47], v[116:119], v[112:115], v[32:47]
	ds_read_b64_tr_b16 v[116:117], v182 offset:33536
	ds_read_b64_tr_b16 v[118:119], v182 offset:34688
	v_exp_f32_e32 v104, v104
	v_exp_f32_e32 v105, v105
	v_exp_f32_e32 v106, v106
	v_exp_f32_e32 v107, v107
	v_exp_f32_e32 v108, v108
	v_exp_f32_e32 v109, v109
	v_exp_f32_e32 v110, v110
	v_exp_f32_e32 v111, v111
	v_pk_add_f32 v[14:15], v[14:15], v[104:105]
	v_pk_add_f32 v[14:15], v[14:15], v[106:107]
	s_waitcnt lgkmcnt(6)
	v_mfma_f32_32x32x16_bf16 v[16:31], v[120:123], v[112:115], v[16:31]
	ds_read_b64_tr_b16 v[120:121], v182 offset:33600
	ds_read_b64_tr_b16 v[122:123], v182 offset:34752
	v_pk_add_f32 v[14:15], v[14:15], v[108:109]
	v_pk_add_f32 v[14:15], v[14:15], v[110:111]
	v_cvt_pk_bf16_f32 v10, v104, v105
	v_cvt_pk_bf16_f32 v11, v106, v107
	v_cvt_pk_bf16_f32 v12, v108, v109
	v_cvt_pk_bf16_f32 v13, v110, v111
	s_waitcnt lgkmcnt(6)
	v_mfma_f32_32x32x16_bf16 v[32:47], v[2:5], v[124:127], v[32:47]
	ds_read_b64_tr_b16 v[2:3], v182 offset:35840
	ds_read_b64_tr_b16 v[4:5], v182 offset:36992
	v_exp_f32_e32 v80, v80
	v_exp_f32_e32 v81, v81
	v_exp_f32_e32 v82, v82
	v_exp_f32_e32 v83, v83
	v_exp_f32_e32 v84, v84
	v_exp_f32_e32 v85, v85
	v_exp_f32_e32 v86, v86
	v_exp_f32_e32 v87, v87
	v_pk_add_f32 v[14:15], v[14:15], v[80:81]
	v_pk_add_f32 v[14:15], v[14:15], v[82:83]
	s_waitcnt lgkmcnt(6)
	v_mfma_f32_32x32x16_bf16 v[16:31], v[6:9], v[124:127], v[16:31]
	ds_read_b64_tr_b16 v[6:7], v182 offset:35904
	ds_read_b64_tr_b16 v[8:9], v182 offset:37056
	v_pk_add_f32 v[14:15], v[14:15], v[84:85]
	v_pk_add_f32 v[14:15], v[14:15], v[86:87]
	v_cvt_pk_bf16_f32 v112, v80, v81
	v_cvt_pk_bf16_f32 v113, v82, v83
	v_cvt_pk_bf16_f32 v114, v84, v85
	v_cvt_pk_bf16_f32 v115, v86, v87
	s_waitcnt lgkmcnt(6)
	v_mfma_f32_32x32x16_bf16 v[32:47], v[116:119], v[10:13], v[32:47]
	ds_read_b64_tr_b16 v[116:117], v182 offset:38144
	ds_read_b64_tr_b16 v[118:119], v182 offset:39296
	v_exp_f32_e32 v88, v88
	v_exp_f32_e32 v89, v89
	v_exp_f32_e32 v90, v90
	v_exp_f32_e32 v91, v91
	v_exp_f32_e32 v92, v92
	v_exp_f32_e32 v93, v93
	v_exp_f32_e32 v94, v94
	v_exp_f32_e32 v95, v95
	v_pk_add_f32 v[14:15], v[14:15], v[88:89]
	v_pk_add_f32 v[14:15], v[14:15], v[90:91]
	s_waitcnt lgkmcnt(6)
	v_mfma_f32_32x32x16_bf16 v[16:31], v[120:123], v[10:13], v[16:31]
	ds_read_b64_tr_b16 v[120:121], v182 offset:38208
	ds_read_b64_tr_b16 v[122:123], v182 offset:39360
	v_pk_add_f32 v[14:15], v[14:15], v[92:93]
	v_pk_add_f32 v[14:15], v[14:15], v[94:95]
	v_cvt_pk_bf16_f32 v124, v88, v89
	v_cvt_pk_bf16_f32 v125, v90, v91
	v_cvt_pk_bf16_f32 v126, v92, v93
	v_cvt_pk_bf16_f32 v127, v94, v95
	s_waitcnt lgkmcnt(6)
	v_mfma_f32_32x32x16_bf16 v[32:47], v[2:5], v[112:115], v[32:47]
	ds_read_b64_tr_b16 v[2:3], v182 offset:40448
	ds_read_b64_tr_b16 v[4:5], v182 offset:41600
	v_exp_f32_e32 v64, v64
	v_exp_f32_e32 v65, v65
	v_exp_f32_e32 v66, v66
	v_exp_f32_e32 v67, v67
	v_exp_f32_e32 v68, v68
	v_exp_f32_e32 v69, v69
	v_exp_f32_e32 v70, v70
	v_exp_f32_e32 v71, v71
	v_pk_add_f32 v[14:15], v[14:15], v[64:65]
	v_pk_add_f32 v[14:15], v[14:15], v[66:67]
	s_waitcnt lgkmcnt(6)
	v_mfma_f32_32x32x16_bf16 v[16:31], v[6:9], v[112:115], v[16:31]
	ds_read_b64_tr_b16 v[6:7], v182 offset:40512
	ds_read_b64_tr_b16 v[8:9], v182 offset:41664
	v_pk_add_f32 v[14:15], v[14:15], v[68:69]
	v_pk_add_f32 v[14:15], v[14:15], v[70:71]
	v_cvt_pk_bf16_f32 v10, v64, v65
	v_cvt_pk_bf16_f32 v11, v66, v67
	v_cvt_pk_bf16_f32 v12, v68, v69
	v_cvt_pk_bf16_f32 v13, v70, v71
	s_waitcnt lgkmcnt(6)
	v_mfma_f32_32x32x16_bf16 v[32:47], v[116:119], v[124:127], v[32:47]
	ds_read_b64_tr_b16 v[116:117], v182 offset:42752
	ds_read_b64_tr_b16 v[118:119], v182 offset:43904
	v_exp_f32_e32 v72, v72
	v_exp_f32_e32 v73, v73
	v_exp_f32_e32 v74, v74
	v_exp_f32_e32 v75, v75
	v_exp_f32_e32 v76, v76
	v_exp_f32_e32 v77, v77
	v_exp_f32_e32 v78, v78
	v_exp_f32_e32 v79, v79
	v_pk_add_f32 v[14:15], v[14:15], v[72:73]
	v_pk_add_f32 v[14:15], v[14:15], v[74:75]
	s_waitcnt lgkmcnt(6)
	v_mfma_f32_32x32x16_bf16 v[16:31], v[120:123], v[124:127], v[16:31]
	ds_read_b64_tr_b16 v[120:121], v182 offset:42816
	ds_read_b64_tr_b16 v[122:123], v182 offset:43968
	v_pk_add_f32 v[14:15], v[14:15], v[76:77]
	v_pk_add_f32 v[14:15], v[14:15], v[78:79]
	v_cvt_pk_bf16_f32 v112, v72, v73
	v_cvt_pk_bf16_f32 v113, v74, v75
	v_cvt_pk_bf16_f32 v114, v76, v77
	v_cvt_pk_bf16_f32 v115, v78, v79
	s_nop 0
	s_waitcnt lgkmcnt(6)
	v_mfma_f32_32x32x16_bf16 v[32:47], v[2:5], v[10:13], v[32:47]
	v_add_f32_e32 v14, v14, v15
	s_waitcnt lgkmcnt(4)
	v_mfma_f32_32x32x16_bf16 v[16:31], v[6:9], v[10:13], v[16:31]
	v_add_f32_e32 v0, v0, v14
	s_waitcnt lgkmcnt(2)
	v_mfma_f32_32x32x16_bf16 v[32:47], v[116:119], v[112:115], v[32:47]
	s_waitcnt lgkmcnt(0)
	v_mfma_f32_32x32x16_bf16 v[16:31], v[120:123], v[112:115], v[16:31]
	s_add_i32 s7, s7, 1
	s_cmp_eq_u32 s7, 64
	s_cbranch_scc1 .Lmla_a_nost
; DI void mla_phase(const Args& A, LAS unsigned char* lds, int i, const int wv) {
;     ...
;             if (j + 1 < 64) MLA_ST((j + 1) & 1);
	s_bitcmp1_b32 s7, 0
	s_cselect_b32 s2, 0xb000, 0
	v_add3_u32 v183, s2, v251, v252
	s_waitcnt vmcnt(4)
	ds_write_b128 v183, v[128:131]
	v_add3_u32 v242, s2, v239, v172
	s_waitcnt vmcnt(3)
	ds_write_b128 v242, v[132:135]
	v_add3_u32 v183, s2, v173, v174
	s_waitcnt vmcnt(2)
	ds_write_b128 v183, v[136:139]
	v_add_u32_e32 v242, s2, v246
	v_add_u32_e32 v183, v242, v175
	v_add_u32_e32 v242, v242, v234
	s_waitcnt vmcnt(1)
	ds_write_b128 v183, v[140:143] offset:26624
	s_waitcnt vmcnt(0)
	ds_write_b128 v242, v[144:147] offset:26624
